# v64 + E2 epilogue: q/k columns and V^T (transposed through LDS) also stored as 16-byte chunks
# speedup vs baseline: 1.0057x; 1.0057x over previous
.LBB0_833:
	s_add_i32 s1, s5, 1
	s_bitcmp1_b32 s1, 0
	s_cselect_b32 s6, 0xe000, 0
	v_add_u32_e32 v246, s6, v102
	s_bitcmp1_b32 s5, 0
	s_cselect_b32 s6, 0xe000, 0
	v_add_u32_e32 v153, s6, v111
	v_add_u32_e32 v154, s6, v106
	s_waitcnt vmcnt(0) lgkmcnt(0)
	s_barrier
	v_add_u32_e32 v181, v153, v108
	ds_read_b128 v[112:115], v181 offset:0x0
	ds_read_b128 v[116:119], v181 offset:0x1000
	v_add_u32_e32 v181, v154, v108
	ds_read_b128 v[120:123], v181 offset:0x0
	ds_read_b128 v[124:127], v181 offset:0x1000
	ds_read_b128 v[130:133], v181 offset:0x2000
	v_mfma_f32_32x32x16_bf16 v[80:95], v[134:137], v[148:151], v[80:95]
	v_mfma_f32_32x32x16_bf16 v[48:63], v[134:137], v[182:185], v[48:63]
	v_lshl_add_u64 v[244:245], v[98:99], 0, s[2:3]
	v_lshl_add_u64 v[244:245], v[244:245], 0, s[90:91]
	v_readfirstlane_b32 s6, v246
	s_mov_b32 m0, s6
	s_nop 0
	global_load_lds_dwordx4 v[244:245], off
	v_mfma_f32_32x32x16_bf16 v[0:15], v[134:137], v[186:189], v[0:15]
	v_mfma_f32_32x32x16_bf16 v[64:79], v[144:147], v[148:151], v[64:79]
	v_add_u32_e32 v243, 0x2000, v246
	v_lshl_add_u64 v[244:245], v[98:99], 0, s[2:3]
	v_lshl_add_u64 v[244:245], v[244:245], 0, s[14:15]
	v_readfirstlane_b32 s6, v243
	s_mov_b32 m0, s6
	s_nop 0
	global_load_lds_dwordx4 v[244:245], off
	v_mfma_f32_32x32x16_bf16 v[32:47], v[144:147], v[182:185], v[32:47]
	v_mfma_f32_32x32x16_bf16 v[16:31], v[144:147], v[186:189], v[16:31]
	v_add_u32_e32 v243, 0x4000, v246
	v_lshl_add_u64 v[244:245], v[98:99], 0, s[2:3]
	v_lshl_add_u64 v[244:245], v[244:245], 0, s[16:17]
	v_readfirstlane_b32 s6, v243
	s_mov_b32 m0, s6
	s_nop 0
	global_load_lds_dwordx4 v[244:245], off
	v_add_u32_e32 v181, v153, v107
	ds_read_b128 v[134:137], v181 offset:0x0
	ds_read_b128 v[144:147], v181 offset:0x1000
	v_add_u32_e32 v181, v154, v107
	ds_read_b128 v[148:151], v181 offset:0x0
	ds_read_b128 v[182:185], v181 offset:0x1000
	ds_read_b128 v[186:189], v181 offset:0x2000
	s_waitcnt lgkmcnt(5)
	v_mfma_f32_32x32x16_bf16 v[80:95], v[112:115], v[120:123], v[80:95]
	v_mfma_f32_32x32x16_bf16 v[48:63], v[112:115], v[124:127], v[48:63]
	v_add_u32_e32 v243, 0x6000, v246
	s_mov_b64 s[6:7], 0x5314080
	v_lshl_add_u64 v[244:245], v[96:97], 0, s[2:3]
	v_lshl_add_u64 v[244:245], v[244:245], 0, s[6:7]
	v_readfirstlane_b32 s6, v243
	s_mov_b32 m0, s6
	s_nop 0
	global_load_lds_dwordx4 v[244:245], off
	v_mfma_f32_32x32x16_bf16 v[0:15], v[112:115], v[130:133], v[0:15]
	v_mfma_f32_32x32x16_bf16 v[64:79], v[116:119], v[120:123], v[64:79]
	v_add_u32_e32 v243, 0x8000, v246
	s_mov_b64 s[6:7], 0x5334080
	v_lshl_add_u64 v[244:245], v[96:97], 0, s[2:3]
	v_lshl_add_u64 v[244:245], v[244:245], 0, s[6:7]
	v_readfirstlane_b32 s6, v243
	s_mov_b32 m0, s6
	s_nop 0
	global_load_lds_dwordx4 v[244:245], off
	v_mfma_f32_32x32x16_bf16 v[32:47], v[116:119], v[124:127], v[32:47]
	v_mfma_f32_32x32x16_bf16 v[16:31], v[116:119], v[130:133], v[16:31]
	v_add_u32_e32 v243, 0xa000, v246
	s_mov_b64 s[6:7], 0x5354080
	v_lshl_add_u64 v[244:245], v[96:97], 0, s[2:3]
	v_lshl_add_u64 v[244:245], v[244:245], 0, s[6:7]
	v_readfirstlane_b32 s6, v243
	s_mov_b32 m0, s6
	s_nop 0
	global_load_lds_dwordx4 v[244:245], off
	v_add_u32_e32 v181, v153, v110
	ds_read_b128 v[112:115], v181 offset:0x0
	ds_read_b128 v[116:119], v181 offset:0x1000
	v_add_u32_e32 v181, v154, v110
	ds_read_b128 v[120:123], v181 offset:0x0
	ds_read_b128 v[124:127], v181 offset:0x1000
	ds_read_b128 v[130:133], v181 offset:0x2000
	s_waitcnt lgkmcnt(5)
	v_mfma_f32_32x32x16_bf16 v[80:95], v[134:137], v[148:151], v[80:95]
	v_mfma_f32_32x32x16_bf16 v[48:63], v[134:137], v[182:185], v[48:63]
	v_add_u32_e32 v243, 0xc000, v246
	s_mov_b64 s[6:7], 0x5374080
	v_lshl_add_u64 v[244:245], v[96:97], 0, s[2:3]
	v_lshl_add_u64 v[244:245], v[244:245], 0, s[6:7]
	v_readfirstlane_b32 s6, v243
	s_mov_b32 m0, s6
	s_nop 0
	global_load_lds_dwordx4 v[244:245], off
	v_mfma_f32_32x32x16_bf16 v[0:15], v[134:137], v[186:189], v[0:15]
	v_mfma_f32_32x32x16_bf16 v[64:79], v[144:147], v[148:151], v[64:79]
	v_mfma_f32_32x32x16_bf16 v[32:47], v[144:147], v[182:185], v[32:47]
	v_mfma_f32_32x32x16_bf16 v[16:31], v[144:147], v[186:189], v[16:31]
	v_add_u32_e32 v181, v153, v109
	ds_read_b128 v[134:137], v181 offset:0x0
	ds_read_b128 v[144:147], v181 offset:0x1000
	v_add_u32_e32 v181, v154, v109
	ds_read_b128 v[148:151], v181 offset:0x0
	ds_read_b128 v[182:185], v181 offset:0x1000
	ds_read_b128 v[186:189], v181 offset:0x2000
	s_waitcnt lgkmcnt(5)
	v_mfma_f32_32x32x16_bf16 v[80:95], v[112:115], v[120:123], v[80:95]
	v_mfma_f32_32x32x16_bf16 v[48:63], v[112:115], v[124:127], v[48:63]
	v_mfma_f32_32x32x16_bf16 v[0:15], v[112:115], v[130:133], v[0:15]
	v_mfma_f32_32x32x16_bf16 v[64:79], v[116:119], v[120:123], v[64:79]
	v_mfma_f32_32x32x16_bf16 v[32:47], v[116:119], v[124:127], v[32:47]
	v_mfma_f32_32x32x16_bf16 v[16:31], v[116:119], v[130:133], v[16:31]
	s_waitcnt lgkmcnt(0)
	s_add_u32 s2, s2, 0x80
	s_addc_u32 s3, s3, 0
	s_mov_b32 s5, s1
	s_cmpk_lg_i32 s2, 0x780
	s_cbranch_scc1 .LBB0_833
	s_bitcmp1_b32 s5, 0
	s_cselect_b32 s6, 0xe000, 0
	v_add_u32_e32 v153, s6, v111
	v_add_u32_e32 v154, s6, v106
	s_waitcnt vmcnt(0) lgkmcnt(0)
	s_barrier
	v_add_u32_e32 v181, v153, v108
	ds_read_b128 v[112:115], v181 offset:0x0
	ds_read_b128 v[116:119], v181 offset:0x1000
	v_add_u32_e32 v181, v154, v108
	ds_read_b128 v[120:123], v181 offset:0x0
	ds_read_b128 v[124:127], v181 offset:0x1000
	ds_read_b128 v[130:133], v181 offset:0x2000
	v_mfma_f32_32x32x16_bf16 v[80:95], v[134:137], v[148:151], v[80:95]
	v_mfma_f32_32x32x16_bf16 v[48:63], v[134:137], v[182:185], v[48:63]
	v_mfma_f32_32x32x16_bf16 v[0:15], v[134:137], v[186:189], v[0:15]
	v_mfma_f32_32x32x16_bf16 v[64:79], v[144:147], v[148:151], v[64:79]
	v_mfma_f32_32x32x16_bf16 v[32:47], v[144:147], v[182:185], v[32:47]
	v_mfma_f32_32x32x16_bf16 v[16:31], v[144:147], v[186:189], v[16:31]
	v_add_u32_e32 v181, v153, v107
	ds_read_b128 v[134:137], v181 offset:0x0
	ds_read_b128 v[144:147], v181 offset:0x1000
	v_add_u32_e32 v181, v154, v107
	ds_read_b128 v[148:151], v181 offset:0x0
	ds_read_b128 v[182:185], v181 offset:0x1000
	ds_read_b128 v[186:189], v181 offset:0x2000
	s_waitcnt lgkmcnt(5)
	v_mfma_f32_32x32x16_bf16 v[80:95], v[112:115], v[120:123], v[80:95]
	v_mfma_f32_32x32x16_bf16 v[48:63], v[112:115], v[124:127], v[48:63]
	v_mfma_f32_32x32x16_bf16 v[0:15], v[112:115], v[130:133], v[0:15]
	v_mfma_f32_32x32x16_bf16 v[64:79], v[116:119], v[120:123], v[64:79]
	v_mfma_f32_32x32x16_bf16 v[32:47], v[116:119], v[124:127], v[32:47]
	v_mfma_f32_32x32x16_bf16 v[16:31], v[116:119], v[130:133], v[16:31]
	v_add_u32_e32 v181, v153, v110
	ds_read_b128 v[112:115], v181 offset:0x0
	ds_read_b128 v[116:119], v181 offset:0x1000
	v_add_u32_e32 v181, v154, v110
	ds_read_b128 v[120:123], v181 offset:0x0
	ds_read_b128 v[124:127], v181 offset:0x1000
	ds_read_b128 v[130:133], v181 offset:0x2000
	s_waitcnt lgkmcnt(5)
	v_mfma_f32_32x32x16_bf16 v[80:95], v[134:137], v[148:151], v[80:95]
	v_mfma_f32_32x32x16_bf16 v[48:63], v[134:137], v[182:185], v[48:63]
	v_mfma_f32_32x32x16_bf16 v[0:15], v[134:137], v[186:189], v[0:15]
	v_mfma_f32_32x32x16_bf16 v[64:79], v[144:147], v[148:151], v[64:79]
	v_mfma_f32_32x32x16_bf16 v[32:47], v[144:147], v[182:185], v[32:47]
	v_mfma_f32_32x32x16_bf16 v[16:31], v[144:147], v[186:189], v[16:31]
	v_add_u32_e32 v181, v153, v109
	ds_read_b128 v[134:137], v181 offset:0x0
	ds_read_b128 v[144:147], v181 offset:0x1000
	v_add_u32_e32 v181, v154, v109
	ds_read_b128 v[148:151], v181 offset:0x0
	ds_read_b128 v[182:185], v181 offset:0x1000
	ds_read_b128 v[186:189], v181 offset:0x2000
	s_waitcnt lgkmcnt(5)
	v_mfma_f32_32x32x16_bf16 v[80:95], v[112:115], v[120:123], v[80:95]
	v_mfma_f32_32x32x16_bf16 v[48:63], v[112:115], v[124:127], v[48:63]
	v_mfma_f32_32x32x16_bf16 v[0:15], v[112:115], v[130:133], v[0:15]
	v_mfma_f32_32x32x16_bf16 v[64:79], v[116:119], v[120:123], v[64:79]
	v_mfma_f32_32x32x16_bf16 v[32:47], v[116:119], v[124:127], v[32:47]
	v_mfma_f32_32x32x16_bf16 v[16:31], v[116:119], v[130:133], v[16:31]
	s_waitcnt lgkmcnt(0)
	v_mfma_f32_32x32x16_bf16 v[80:95], v[134:137], v[148:151], v[80:95]
	v_mfma_f32_32x32x16_bf16 v[48:63], v[134:137], v[182:185], v[48:63]
	v_mfma_f32_32x32x16_bf16 v[0:15], v[134:137], v[186:189], v[0:15]
	v_mfma_f32_32x32x16_bf16 v[64:79], v[144:147], v[148:151], v[64:79]
	v_mfma_f32_32x32x16_bf16 v[32:47], v[144:147], v[182:185], v[32:47]
	v_mfma_f32_32x32x16_bf16 v[16:31], v[144:147], v[186:189], v[16:31]
	v_or_b32_e32 v97, s26, v101
	s_cmp_lt_i32 s4, 22
	v_add_u32_e32 v116, v104, v97
	s_cselect_b64 s[2:3], -1, 0
	s_cmp_gt_i32 s4, 21
	v_add_u32_e32 v112, s0, v103
	s_cselect_b64 s[14:15], -1, 0
	s_add_i32 s27, s26, 0xfffff000
	v_lshlrev_b32_e32 v97, 2, v103
	v_lshlrev_b32_e32 v98, 4, v100
	s_mov_b32 s0, 0x24300
	v_add_u32_e32 v113, 0xfffff000, v116
	v_add3_u32 v120, v97, v98, s0
	v_xor_b32_e32 v97, s27, v113
	s_movk_i32 s4, 0x400
	v_cmp_gt_u32_e64 s[42:43], s4, v97
	s_and_b64 s[4:5], s[14:15], s[42:43]
	v_cndmask_b32_e64 v121, 0, 1, s[2:3]
	s_movk_i32 s2, 0x1000
	v_cndmask_b32_e64 v97, 0, 1, s[4:5]
	v_cmp_gt_i32_e64 s[42:43], s2, v116
	v_ashrrev_i32_e32 v96, 9, v112
	v_cmp_eq_u32_e32 vcc, 4, v96
	v_cndmask_b32_e64 v97, v97, v121, s[42:43]
	v_and_b32_e32 v97, 1, v97
	v_cmp_lt_i32_e64 s[40:41], 2, v96
	v_cmp_lt_u32_e64 s[0:1], 4, v96
	v_cndmask_b32_e32 v96, v178, v179, vcc
	v_cmp_eq_u32_e64 s[44:45], 1, v97
	v_add_u32_e32 v108, v96, v112
	v_subrev_u32_e32 v96, s26, v116
	v_cndmask_b32_e64 v97, v171, 0, s[44:45]
	v_lshl_add_u32 v96, v96, 2, v167
	v_add_u32_e32 v117, v120, v97
	s_barrier
	v_lshlrev_b32_e32 v118, 2, v100
	ds_read_b32 v126, v96
	ds_read_b128 v[96:99], v117
	ds_read_b128 v[100:103], v117 offset:32
	ds_read_b128 v[122:125], v117 offset:64
	v_add_u32_e32 v110, 0xfffff600, v112
	s_movk_i32 s2, 0xfff
	s_waitcnt lgkmcnt(2)
	v_pk_fma_f32 v[104:105], v[80:81], v[126:127], v[96:97] op_sel_hi:[1,0,1]
	v_pk_fma_f32 v[106:107], v[82:83], v[126:127], v[98:99] op_sel_hi:[1,0,1]
	s_waitcnt lgkmcnt(1)
	v_pk_fma_f32 v[100:101], v[84:85], v[126:127], v[100:101] op_sel_hi:[1,0,1]
	ds_read_b128 v[80:83], v117 offset:96
	v_pk_fma_f32 v[102:103], v[86:87], v[126:127], v[102:103] op_sel_hi:[1,0,1]
	ds_read_b128 v[84:87], v117 offset:128
	s_waitcnt lgkmcnt(2)
	v_pk_fma_f32 v[96:97], v[88:89], v[126:127], v[122:123] op_sel_hi:[1,0,1]
	v_pk_fma_f32 v[98:99], v[90:91], v[126:127], v[124:125] op_sel_hi:[1,0,1]
	s_waitcnt lgkmcnt(1)
	v_pk_fma_f32 v[88:89], v[92:93], v[126:127], v[80:81] op_sel_hi:[1,0,1]
	v_pk_fma_f32 v[90:91], v[94:95], v[126:127], v[82:83] op_sel_hi:[1,0,1]
	ds_read_b128 v[80:83], v117 offset:160
	ds_read_b128 v[92:95], v117 offset:192
	s_waitcnt lgkmcnt(2)
	v_pk_fma_f32 v[84:85], v[64:65], v[126:127], v[84:85] op_sel_hi:[1,0,1]
	v_pk_fma_f32 v[86:87], v[66:67], v[126:127], v[86:87] op_sel_hi:[1,0,1]
	ds_read_b128 v[64:67], v117 offset:224
	v_ashrrev_i32_e32 v119, 6, v110
	v_ashrrev_i32_e32 v111, 31, v110
	v_ashrrev_i32_e32 v109, 31, v108
	v_mov_b32_e32 v114, v112
	v_mov_b32_e32 v115, v129
	v_cmp_lt_i32_e64 s[44:45], s2, v116
	s_waitcnt lgkmcnt(2)
	v_pk_fma_f32 v[80:81], v[68:69], v[126:127], v[80:81] op_sel_hi:[1,0,1]
	v_pk_fma_f32 v[82:83], v[70:71], v[126:127], v[82:83] op_sel_hi:[1,0,1]
	s_waitcnt lgkmcnt(1)
	v_pk_fma_f32 v[68:69], v[72:73], v[126:127], v[92:93] op_sel_hi:[1,0,1]
	v_pk_fma_f32 v[70:71], v[74:75], v[126:127], v[94:95] op_sel_hi:[1,0,1]
	s_waitcnt lgkmcnt(0)
	v_pk_fma_f32 v[64:65], v[76:77], v[126:127], v[64:65] op_sel_hi:[1,0,1]
	v_pk_fma_f32 v[66:67], v[78:79], v[126:127], v[66:67] op_sel_hi:[1,0,1]
	s_and_saveexec_b64 s[2:3], s[40:41]
	s_xor_b64 s[2:3], exec, s[2:3]
	s_cbranch_execz .LBB0_880
	s_and_saveexec_b64 s[4:5], s[0:1]
	s_xor_b64 s[4:5], exec, s[4:5]
	s_cbranch_execz .LBB0_859
	v_mov_b64_e32 v[72:73], 0
	s_and_saveexec_b64 s[6:7], s[42:43]
	v_lshrrev_b32_e32 v72, 7, v116
	v_and_b32_e32 v72, 0xfffffe, v72
	v_add_u32_e32 v72, s48, v72
	s_mov_b32 s13, 0x6050400
	v_perm_b32 v72, v72, v116, s13
	v_ashrrev_i32_e32 v73, 31, v72
	v_lshlrev_b64 v[72:73], 11, v[72:73]
	v_lshl_add_u64 v[72:73], s[62:63], 0, v[72:73]
	v_lshl_add_u64 v[72:73], v[110:111], 2, v[72:73]
	s_or_b64 exec, exec, s[6:7]
	s_and_saveexec_b64 s[6:7], s[44:45]
	s_xor_b64 s[6:7], exec, s[6:7]
	v_lshrrev_b32_e32 v74, 7, v113
	v_and_b32_e32 v92, 0x1fffff8, v74
	s_or_saveexec_b64 s[6:7], s[6:7]
	v_mov_b64_e32 v[74:75], 0x400
	v_mov_b32_e32 v75, 0x3ff
	v_mov_b64_e32 v[76:77], 0xdf94000
	v_mov_b64_e32 v[78:79], 17
	s_xor_b64 exec, exec, s[6:7]
	v_ashrrev_i32_e32 v74, 5, v116
	v_and_b32_e32 v92, -8, v74
	v_mov_b64_e32 v[74:75], 0x100
	v_mov_b32_e32 v75, 0xff
	v_mov_b64_e32 v[76:77], 0xdb94000
	v_mov_b64_e32 v[78:79], 15
	s_or_b64 exec, exec, s[6:7]
	v_add_u32_e32 v92, v92, v119
	v_ashrrev_i32_e32 v93, 31, v92
	v_lshl_add_u64 v[76:77], s[50:51], 0, v[76:77]
	v_lshlrev_b64 v[78:79], v78, v[92:93]
	v_and_b32_e32 v75, v75, v116
	v_lshl_add_u64 v[76:77], v[76:77], 0, v[78:79]
	v_lshlrev_b32_e32 v128, 1, v75
	v_mul_u32_u24_e32 v75, v74, v118
	v_lshl_add_u64 v[76:77], v[76:77], 0, v[128:129]
	v_lshlrev_b32_e32 v128, 1, v75
	v_lshl_add_u64 v[78:79], v[76:77], 0, v[128:129]
	v_cvt_pk_bf16_f32 v75, v104, s0
	v_and_b32_e32 v240, 31, v155
	v_lshrrev_b32_e32 v239, 6, v155
	v_mul_u32_u24_e32 v239, 0x1400, v239
	v_bfe_u32 v246, v155, 5, 1
	v_mul_u32_u24_e32 v246, 0x140, v246
	v_lshl_add_u32 v238, v240, 1, v239
	v_add_u32_e32 v238, v238, v246
	v_bfe_u32 v246, v155, 2, 4
	v_mul_u32_u24_e32 v247, 0x50, v246
	v_add_u32_e32 v239, v239, v247
	v_mul_u32_u24_e32 v246, v74, v246
	v_and_b32_e32 v247, 3, v155
	v_lshl_add_u32 v239, v247, 4, v239
	v_lshlrev_b32_e32 v247, 4, v247
	v_lshl_add_u32 v246, v246, 1, v247
	v_lshlrev_b32_e32 v240, 1, v240
	v_sub_u32_e32 v246, v246, v240
	v_ashrrev_i32_e32 v247, 31, v246
	v_lshl_add_u64 v[244:245], v[76:77], 0, v[246:247]
	v_lshlrev_b32_e32 v246, 5, v74
	v_mov_b32_e32 v247, 0
	ds_write_b16 v238, v75
	v_or_b32_e32 v75, 1, v118
	v_mul_u32_u24_e32 v75, v74, v75
	v_lshlrev_b32_e32 v128, 1, v75
	v_lshl_add_u64 v[78:79], v[76:77], 0, v[128:129]
	v_cvt_pk_bf16_f32 v75, v105, s0
	ds_write_b16 v238, v75 offset:80
	v_or_b32_e32 v75, 2, v118
	v_mul_u32_u24_e32 v75, v74, v75
	v_lshlrev_b32_e32 v128, 1, v75
	v_lshl_add_u64 v[78:79], v[76:77], 0, v[128:129]
	v_cvt_pk_bf16_f32 v75, v106, s0
	ds_write_b16 v238, v75 offset:160
	v_or_b32_e32 v75, 3, v118
	v_mul_u32_u24_e32 v75, v74, v75
	v_lshlrev_b32_e32 v128, 1, v75
	v_lshl_add_u64 v[78:79], v[76:77], 0, v[128:129]
	v_cvt_pk_bf16_f32 v75, v107, s0
	ds_write_b16 v238, v75 offset:240
	s_and_saveexec_b64 s[6:7], s[42:43]
	s_cbranch_execz .LBB0_844
	v_lshlrev_b32_e32 v128, 2, v118
	v_lshl_add_u64 v[78:79], v[72:73], 0, v[128:129]
	global_store_dwordx4 v[78:79], v[104:107], off
.LBB0_844:
	s_or_b64 exec, exec, s[6:7]
	v_or_b32_e32 v75, 8, v118
	v_mul_u32_u24_e32 v75, v74, v75
	v_lshlrev_b32_e32 v128, 1, v75
	v_lshl_add_u64 v[78:79], v[76:77], 0, v[128:129]
	v_cvt_pk_bf16_f32 v75, v100, s0
	ds_write_b16 v238, v75 offset:640
	v_or_b32_e32 v75, 9, v118
	v_mul_u32_u24_e32 v75, v74, v75
	v_lshlrev_b32_e32 v128, 1, v75
	v_lshl_add_u64 v[78:79], v[76:77], 0, v[128:129]
	v_cvt_pk_bf16_f32 v75, v101, s0
	ds_write_b16 v238, v75 offset:720
	v_or_b32_e32 v75, 10, v118
	v_mul_u32_u24_e32 v75, v74, v75
	v_lshlrev_b32_e32 v128, 1, v75
	v_lshl_add_u64 v[78:79], v[76:77], 0, v[128:129]
	v_cvt_pk_bf16_f32 v75, v102, s0
	ds_write_b16 v238, v75 offset:800
	v_or_b32_e32 v75, 11, v118
	v_mul_u32_u24_e32 v75, v74, v75
	v_lshlrev_b32_e32 v128, 1, v75
	v_lshl_add_u64 v[78:79], v[76:77], 0, v[128:129]
	v_cvt_pk_bf16_f32 v75, v103, s0
	ds_write_b16 v238, v75 offset:880
	s_and_saveexec_b64 s[6:7], s[42:43]
	s_cbranch_execz .LBB0_846
	v_lshlrev_b32_e32 v128, 2, v118
	v_lshl_add_u64 v[78:79], v[72:73], 0, v[128:129]
	global_store_dwordx4 v[78:79], v[100:103], off offset:32
.LBB0_846:
	s_or_b64 exec, exec, s[6:7]
	v_or_b32_e32 v75, 16, v118
	v_mul_u32_u24_e32 v75, v74, v75
	v_lshlrev_b32_e32 v128, 1, v75
	v_lshl_add_u64 v[78:79], v[76:77], 0, v[128:129]
	v_cvt_pk_bf16_f32 v75, v96, s0
	ds_write_b16 v238, v75 offset:1280
	v_or_b32_e32 v75, 17, v118
	v_mul_u32_u24_e32 v75, v74, v75
	v_lshlrev_b32_e32 v128, 1, v75
	v_lshl_add_u64 v[78:79], v[76:77], 0, v[128:129]
	v_cvt_pk_bf16_f32 v75, v97, s0
	ds_write_b16 v238, v75 offset:1360
	v_or_b32_e32 v75, 18, v118
	v_mul_u32_u24_e32 v75, v74, v75
	v_lshlrev_b32_e32 v128, 1, v75
	v_lshl_add_u64 v[78:79], v[76:77], 0, v[128:129]
	v_cvt_pk_bf16_f32 v75, v98, s0
	ds_write_b16 v238, v75 offset:1440
	v_or_b32_e32 v75, 19, v118
	v_mul_u32_u24_e32 v75, v74, v75
	v_lshlrev_b32_e32 v128, 1, v75
	v_lshl_add_u64 v[78:79], v[76:77], 0, v[128:129]
	v_cvt_pk_bf16_f32 v75, v99, s0
	ds_write_b16 v238, v75 offset:1520
	s_and_saveexec_b64 s[6:7], s[42:43]
	s_cbranch_execz .LBB0_848
	v_lshlrev_b32_e32 v128, 2, v118
	v_lshl_add_u64 v[78:79], v[72:73], 0, v[128:129]
	global_store_dwordx4 v[78:79], v[96:99], off offset:64
.LBB0_848:
	s_or_b64 exec, exec, s[6:7]
	v_or_b32_e32 v75, 24, v118
	v_mul_u32_u24_e32 v75, v74, v75
	v_lshlrev_b32_e32 v128, 1, v75
	v_lshl_add_u64 v[78:79], v[76:77], 0, v[128:129]
	v_cvt_pk_bf16_f32 v75, v88, s0
	ds_write_b16 v238, v75 offset:1920
	v_or_b32_e32 v75, 25, v118
	v_mul_u32_u24_e32 v75, v74, v75
	v_lshlrev_b32_e32 v128, 1, v75
	v_lshl_add_u64 v[78:79], v[76:77], 0, v[128:129]
	v_cvt_pk_bf16_f32 v75, v89, s0
	ds_write_b16 v238, v75 offset:2000
	v_or_b32_e32 v75, 26, v118
	v_mul_u32_u24_e32 v75, v74, v75
	v_lshlrev_b32_e32 v128, 1, v75
	v_lshl_add_u64 v[78:79], v[76:77], 0, v[128:129]
	v_cvt_pk_bf16_f32 v75, v90, s0
	ds_write_b16 v238, v75 offset:2080
	v_or_b32_e32 v75, 27, v118
	v_mul_u32_u24_e32 v75, v74, v75
	v_lshlrev_b32_e32 v128, 1, v75
	v_lshl_add_u64 v[78:79], v[76:77], 0, v[128:129]
	v_cvt_pk_bf16_f32 v75, v91, s0
	ds_write_b16 v238, v75 offset:2160
	s_and_saveexec_b64 s[6:7], s[42:43]
	s_cbranch_execz .LBB0_850
	v_lshlrev_b32_e32 v128, 2, v118
	v_lshl_add_u64 v[78:79], v[72:73], 0, v[128:129]
	global_store_dwordx4 v[78:79], v[88:91], off offset:96
.LBB0_850:
	s_or_b64 exec, exec, s[6:7]
	v_or_b32_e32 v75, 32, v118
	v_mul_u32_u24_e32 v75, v74, v75
	v_lshlrev_b32_e32 v128, 1, v75
	v_lshl_add_u64 v[78:79], v[76:77], 0, v[128:129]
	v_cvt_pk_bf16_f32 v75, v84, s0
	ds_write_b16 v238, v75 offset:2560
	v_or_b32_e32 v75, 33, v118
	v_mul_u32_u24_e32 v75, v74, v75
	v_lshlrev_b32_e32 v128, 1, v75
	v_lshl_add_u64 v[78:79], v[76:77], 0, v[128:129]
	v_cvt_pk_bf16_f32 v75, v85, s0
	ds_write_b16 v238, v75 offset:2640
	v_or_b32_e32 v75, 34, v118
	v_mul_u32_u24_e32 v75, v74, v75
	v_lshlrev_b32_e32 v128, 1, v75
	v_lshl_add_u64 v[78:79], v[76:77], 0, v[128:129]
	v_cvt_pk_bf16_f32 v75, v86, s0
	ds_write_b16 v238, v75 offset:2720
	v_or_b32_e32 v75, 35, v118
	v_mul_u32_u24_e32 v75, v74, v75
	v_lshlrev_b32_e32 v128, 1, v75
	v_lshl_add_u64 v[78:79], v[76:77], 0, v[128:129]
	v_cvt_pk_bf16_f32 v75, v87, s0
	ds_write_b16 v238, v75 offset:2800
	s_and_saveexec_b64 s[6:7], s[42:43]
	s_cbranch_execz .LBB0_852
	v_lshlrev_b32_e32 v128, 2, v118
	v_lshl_add_u64 v[78:79], v[72:73], 0, v[128:129]
	global_store_dwordx4 v[78:79], v[84:87], off offset:128
.LBB0_852:
	s_or_b64 exec, exec, s[6:7]
	v_or_b32_e32 v75, 40, v118
	v_mul_u32_u24_e32 v75, v74, v75
	v_lshlrev_b32_e32 v128, 1, v75
	v_lshl_add_u64 v[78:79], v[76:77], 0, v[128:129]
	v_cvt_pk_bf16_f32 v75, v80, s0
	ds_write_b16 v238, v75 offset:3200
	v_or_b32_e32 v75, 41, v118
	v_mul_u32_u24_e32 v75, v74, v75
	v_lshlrev_b32_e32 v128, 1, v75
	v_lshl_add_u64 v[78:79], v[76:77], 0, v[128:129]
	v_cvt_pk_bf16_f32 v75, v81, s0
	ds_write_b16 v238, v75 offset:3280
	v_or_b32_e32 v75, 42, v118
	v_mul_u32_u24_e32 v75, v74, v75
	v_lshlrev_b32_e32 v128, 1, v75
	v_lshl_add_u64 v[78:79], v[76:77], 0, v[128:129]
	v_cvt_pk_bf16_f32 v75, v82, s0
	ds_write_b16 v238, v75 offset:3360
	v_or_b32_e32 v75, 43, v118
	v_mul_u32_u24_e32 v75, v74, v75
	v_lshlrev_b32_e32 v128, 1, v75
	v_lshl_add_u64 v[78:79], v[76:77], 0, v[128:129]
	v_cvt_pk_bf16_f32 v75, v83, s0
	ds_write_b16 v238, v75 offset:3440
	s_and_saveexec_b64 s[6:7], s[42:43]
	s_cbranch_execz .LBB0_854
	v_lshlrev_b32_e32 v128, 2, v118
	v_lshl_add_u64 v[78:79], v[72:73], 0, v[128:129]
	global_store_dwordx4 v[78:79], v[80:83], off offset:160
.LBB0_854:
	s_or_b64 exec, exec, s[6:7]
	v_or_b32_e32 v75, 48, v118
	v_mul_u32_u24_e32 v75, v74, v75
	v_lshlrev_b32_e32 v128, 1, v75
	v_lshl_add_u64 v[78:79], v[76:77], 0, v[128:129]
	v_cvt_pk_bf16_f32 v75, v68, s0
	ds_write_b16 v238, v75 offset:3840
	v_or_b32_e32 v75, 49, v118
	v_mul_u32_u24_e32 v75, v74, v75
	v_lshlrev_b32_e32 v128, 1, v75
	v_lshl_add_u64 v[78:79], v[76:77], 0, v[128:129]
	v_cvt_pk_bf16_f32 v75, v69, s0
	ds_write_b16 v238, v75 offset:3920
	v_or_b32_e32 v75, 50, v118
	v_mul_u32_u24_e32 v75, v74, v75
	v_lshlrev_b32_e32 v128, 1, v75
	v_lshl_add_u64 v[78:79], v[76:77], 0, v[128:129]
	v_cvt_pk_bf16_f32 v75, v70, s0
	ds_write_b16 v238, v75 offset:4000
	v_or_b32_e32 v75, 51, v118
	v_mul_u32_u24_e32 v75, v74, v75
	v_lshlrev_b32_e32 v128, 1, v75
	v_lshl_add_u64 v[78:79], v[76:77], 0, v[128:129]
	v_cvt_pk_bf16_f32 v75, v71, s0
	ds_write_b16 v238, v75 offset:4080
	s_and_saveexec_b64 s[6:7], s[42:43]
	s_cbranch_execz .LBB0_856
	v_lshlrev_b32_e32 v128, 2, v118
	v_lshl_add_u64 v[78:79], v[72:73], 0, v[128:129]
	global_store_dwordx4 v[78:79], v[68:71], off offset:192
.LBB0_856:
	s_or_b64 exec, exec, s[6:7]
	s_nop 0
	v_or_b32_e32 v68, 56, v118
	v_mul_u32_u24_e32 v68, v74, v68
	v_lshlrev_b32_e32 v128, 1, v68
	v_lshl_add_u64 v[68:69], v[76:77], 0, v[128:129]
	v_cvt_pk_bf16_f32 v70, v64, s0
	ds_write_b16 v238, v70 offset:4480
	v_or_b32_e32 v68, 57, v118
	v_mul_u32_u24_e32 v68, v74, v68
	v_lshlrev_b32_e32 v128, 1, v68
	v_lshl_add_u64 v[68:69], v[76:77], 0, v[128:129]
	v_cvt_pk_bf16_f32 v70, v65, s0
	ds_write_b16 v238, v70 offset:4560
	v_or_b32_e32 v68, 58, v118
	v_mul_u32_u24_e32 v68, v74, v68
	v_lshlrev_b32_e32 v128, 1, v68
	v_lshl_add_u64 v[68:69], v[76:77], 0, v[128:129]
	v_cvt_pk_bf16_f32 v70, v66, s0
	ds_write_b16 v238, v70 offset:4640
	v_or_b32_e32 v68, 59, v118
	v_mul_u32_u24_e32 v68, v74, v68
	v_lshlrev_b32_e32 v128, 1, v68
	v_lshl_add_u64 v[68:69], v[76:77], 0, v[128:129]
	v_cvt_pk_bf16_f32 v70, v67, s0
	ds_write_b16 v238, v70 offset:4720
	s_waitcnt lgkmcnt(0)
	ds_read_b128 v[230:233], v239 offset:0
	ds_read_b128 v[234:237], v239 offset:1280
	ds_read_b128 v[182:185], v239 offset:2560
	ds_read_b128 v[186:189], v239 offset:3840
	s_waitcnt lgkmcnt(3)
	global_store_dwordx4 v[244:245], v[230:233], off
	v_lshl_add_u64 v[244:245], v[244:245], 0, v[246:247]
	s_waitcnt lgkmcnt(2)
	global_store_dwordx4 v[244:245], v[234:237], off
	v_lshl_add_u64 v[244:245], v[244:245], 0, v[246:247]
	s_waitcnt lgkmcnt(1)
	global_store_dwordx4 v[244:245], v[182:185], off
	v_lshl_add_u64 v[244:245], v[244:245], 0, v[246:247]
	s_waitcnt lgkmcnt(0)
	global_store_dwordx4 v[244:245], v[186:189], off
	s_and_saveexec_b64 s[6:7], s[42:43]
	s_cbranch_execz .LBB0_858
	v_lshlrev_b32_e32 v128, 2, v118
	v_lshl_add_u64 v[68:69], v[72:73], 0, v[128:129]
	global_store_dwordx4 v[68:69], v[64:67], off offset:224

.LBB0_882:
	s_or_b64 exec, exec, s[2:3]
	v_add_u32_e32 v78, 32, v116
	v_subrev_u32_e32 v64, s26, v78
	s_movk_i32 s2, 0xfdf
	v_lshl_add_u32 v64, v64, 2, v167
	v_cmp_lt_i32_e64 s[44:45], s2, v116
	s_movk_i32 s2, 0xfe0
	v_add_u32_e32 v77, 0xfffff020, v116
	ds_read_b32 v80, v64
	v_cmp_gt_i32_e64 s[42:43], s2, v116
	v_xor_b32_e32 v64, s27, v77
	s_movk_i32 s2, 0x400
	v_cmp_gt_u32_e64 s[46:47], s2, v64
	s_and_b64 s[2:3], s[14:15], s[46:47]
	v_cndmask_b32_e64 v64, 0, 1, s[2:3]
	v_cndmask_b32_e64 v64, v64, v121, s[42:43]
	v_and_b32_e32 v64, 1, v64
	v_cmp_eq_u32_e64 s[46:47], 1, v64
	s_nop 1
	v_cndmask_b32_e64 v64, v171, 0, s[46:47]
	v_add_u32_e32 v79, v120, v64
	ds_read_b128 v[64:67], v79
	ds_read_b128 v[68:71], v79 offset:32
	s_waitcnt lgkmcnt(1)
	v_pk_fma_f32 v[72:73], v[48:49], v[80:81], v[64:65] op_sel_hi:[1,0,1]
	v_pk_fma_f32 v[74:75], v[50:51], v[80:81], v[66:67] op_sel_hi:[1,0,1]
	ds_read_b128 v[48:51], v79 offset:64
	s_waitcnt lgkmcnt(1)
	v_pk_fma_f32 v[68:69], v[52:53], v[80:81], v[68:69] op_sel_hi:[1,0,1]
	v_pk_fma_f32 v[70:71], v[54:55], v[80:81], v[70:71] op_sel_hi:[1,0,1]
	s_waitcnt lgkmcnt(0)
	v_pk_fma_f32 v[64:65], v[56:57], v[80:81], v[48:49] op_sel_hi:[1,0,1]
	v_pk_fma_f32 v[66:67], v[58:59], v[80:81], v[50:51] op_sel_hi:[1,0,1]
	ds_read_b128 v[48:51], v79 offset:96
	s_waitcnt lgkmcnt(0)
	v_pk_fma_f32 v[56:57], v[60:61], v[80:81], v[48:49] op_sel_hi:[1,0,1]
	v_pk_fma_f32 v[58:59], v[62:63], v[80:81], v[50:51] op_sel_hi:[1,0,1]
	ds_read_b128 v[48:51], v79 offset:128
	s_waitcnt lgkmcnt(0)
	v_pk_fma_f32 v[52:53], v[32:33], v[80:81], v[48:49] op_sel_hi:[1,0,1]
	v_pk_fma_f32 v[54:55], v[34:35], v[80:81], v[50:51] op_sel_hi:[1,0,1]
	ds_read_b128 v[32:35], v79 offset:160
	s_waitcnt lgkmcnt(0)
	v_pk_fma_f32 v[48:49], v[36:37], v[80:81], v[32:33] op_sel_hi:[1,0,1]
	v_pk_fma_f32 v[50:51], v[38:39], v[80:81], v[34:35] op_sel_hi:[1,0,1]
	ds_read_b128 v[32:35], v79 offset:192
	s_waitcnt lgkmcnt(0)
	v_pk_fma_f32 v[36:37], v[40:41], v[80:81], v[32:33] op_sel_hi:[1,0,1]
	v_pk_fma_f32 v[38:39], v[42:43], v[80:81], v[34:35] op_sel_hi:[1,0,1]
	ds_read_b128 v[32:35], v79 offset:224
	s_waitcnt lgkmcnt(0)
	v_pk_fma_f32 v[32:33], v[44:45], v[80:81], v[32:33] op_sel_hi:[1,0,1]
	v_pk_fma_f32 v[34:35], v[46:47], v[80:81], v[34:35] op_sel_hi:[1,0,1]
	s_and_saveexec_b64 s[2:3], s[40:41]
	s_xor_b64 s[2:3], exec, s[2:3]
	s_cbranch_execz .LBB0_928
	s_and_saveexec_b64 s[4:5], s[0:1]
	s_xor_b64 s[4:5], exec, s[4:5]
	s_cbranch_execz .LBB0_907
	v_mov_b64_e32 v[40:41], 0
	s_and_saveexec_b64 s[6:7], s[42:43]
	v_lshrrev_b32_e32 v40, 7, v78
	v_and_b32_e32 v40, 0xfffffe, v40
	v_add_u32_e32 v40, s48, v40
	s_mov_b32 s13, 0x6050400
	v_perm_b32 v40, v40, v78, s13
	v_ashrrev_i32_e32 v41, 31, v40
	v_lshlrev_b64 v[40:41], 11, v[40:41]
	v_lshl_add_u64 v[40:41], s[62:63], 0, v[40:41]
	v_lshl_add_u64 v[40:41], v[110:111], 2, v[40:41]
	s_or_b64 exec, exec, s[6:7]
	s_and_saveexec_b64 s[6:7], s[44:45]
	s_xor_b64 s[6:7], exec, s[6:7]
	v_lshrrev_b32_e32 v42, 7, v77
	v_and_b32_e32 v60, 0x1fffff8, v42
	s_or_saveexec_b64 s[6:7], s[6:7]
	v_mov_b64_e32 v[42:43], 0x400
	v_mov_b32_e32 v43, 0x3ff
	v_mov_b64_e32 v[44:45], 0xdf94000
	v_mov_b64_e32 v[46:47], 17
	s_xor_b64 exec, exec, s[6:7]
	v_ashrrev_i32_e32 v42, 5, v78
	v_and_b32_e32 v60, -8, v42
	v_mov_b64_e32 v[42:43], 0x100
	v_mov_b32_e32 v43, 0xff
	v_mov_b64_e32 v[44:45], 0xdb94000
	v_mov_b64_e32 v[46:47], 15
	s_or_b64 exec, exec, s[6:7]
	v_add_u32_e32 v60, v60, v119
	v_ashrrev_i32_e32 v61, 31, v60
	v_lshl_add_u64 v[44:45], s[50:51], 0, v[44:45]
	v_lshlrev_b64 v[46:47], v46, v[60:61]
	v_and_b32_e32 v43, v43, v78
	v_lshl_add_u64 v[44:45], v[44:45], 0, v[46:47]
	v_lshlrev_b32_e32 v128, 1, v43
	v_mul_u32_u24_e32 v43, v42, v118
	v_lshl_add_u64 v[44:45], v[44:45], 0, v[128:129]
	v_lshlrev_b32_e32 v128, 1, v43
	v_lshl_add_u64 v[46:47], v[44:45], 0, v[128:129]
	v_cvt_pk_bf16_f32 v43, v72, s0
	v_and_b32_e32 v240, 31, v155
	v_lshrrev_b32_e32 v239, 6, v155
	v_mul_u32_u24_e32 v239, 0x1400, v239
	v_bfe_u32 v246, v155, 5, 1
	v_mul_u32_u24_e32 v246, 0x140, v246
	v_lshl_add_u32 v238, v240, 1, v239
	v_add_u32_e32 v238, v238, v246
	v_bfe_u32 v246, v155, 2, 4
	v_mul_u32_u24_e32 v247, 0x50, v246
	v_add_u32_e32 v239, v239, v247
	v_mul_u32_u24_e32 v246, v42, v246
	v_and_b32_e32 v247, 3, v155
	v_lshl_add_u32 v239, v247, 4, v239
	v_lshlrev_b32_e32 v247, 4, v247
	v_lshl_add_u32 v246, v246, 1, v247
	v_lshlrev_b32_e32 v240, 1, v240
	v_sub_u32_e32 v246, v246, v240
	v_ashrrev_i32_e32 v247, 31, v246
	v_lshl_add_u64 v[244:245], v[44:45], 0, v[246:247]
	v_lshlrev_b32_e32 v246, 5, v42
	v_mov_b32_e32 v247, 0
	ds_write_b16 v238, v43
	v_or_b32_e32 v43, 1, v118
	v_mul_u32_u24_e32 v43, v42, v43
	v_lshlrev_b32_e32 v128, 1, v43
	v_lshl_add_u64 v[46:47], v[44:45], 0, v[128:129]
	v_cvt_pk_bf16_f32 v43, v73, s0
	ds_write_b16 v238, v43 offset:80
	v_or_b32_e32 v43, 2, v118
	v_mul_u32_u24_e32 v43, v42, v43
	v_lshlrev_b32_e32 v128, 1, v43
	v_lshl_add_u64 v[46:47], v[44:45], 0, v[128:129]
	v_cvt_pk_bf16_f32 v43, v74, s0
	ds_write_b16 v238, v43 offset:160
	v_or_b32_e32 v43, 3, v118
	v_mul_u32_u24_e32 v43, v42, v43
	v_lshlrev_b32_e32 v128, 1, v43
	v_lshl_add_u64 v[46:47], v[44:45], 0, v[128:129]
	v_cvt_pk_bf16_f32 v43, v75, s0
	ds_write_b16 v238, v43 offset:240
	s_and_saveexec_b64 s[6:7], s[42:43]
	s_cbranch_execz .LBB0_892
	v_lshlrev_b32_e32 v128, 2, v118
	v_lshl_add_u64 v[46:47], v[40:41], 0, v[128:129]
	global_store_dwordx4 v[46:47], v[72:75], off
.LBB0_892:
	s_or_b64 exec, exec, s[6:7]
	v_or_b32_e32 v43, 8, v118
	v_mul_u32_u24_e32 v43, v42, v43
	v_lshlrev_b32_e32 v128, 1, v43
	v_lshl_add_u64 v[46:47], v[44:45], 0, v[128:129]
	v_cvt_pk_bf16_f32 v43, v68, s0
	ds_write_b16 v238, v43 offset:640
	v_or_b32_e32 v43, 9, v118
	v_mul_u32_u24_e32 v43, v42, v43
	v_lshlrev_b32_e32 v128, 1, v43
	v_lshl_add_u64 v[46:47], v[44:45], 0, v[128:129]
	v_cvt_pk_bf16_f32 v43, v69, s0
	ds_write_b16 v238, v43 offset:720
	v_or_b32_e32 v43, 10, v118
	v_mul_u32_u24_e32 v43, v42, v43
	v_lshlrev_b32_e32 v128, 1, v43
	v_lshl_add_u64 v[46:47], v[44:45], 0, v[128:129]
	v_cvt_pk_bf16_f32 v43, v70, s0
	ds_write_b16 v238, v43 offset:800
	v_or_b32_e32 v43, 11, v118
	v_mul_u32_u24_e32 v43, v42, v43
	v_lshlrev_b32_e32 v128, 1, v43
	v_lshl_add_u64 v[46:47], v[44:45], 0, v[128:129]
	v_cvt_pk_bf16_f32 v43, v71, s0
	ds_write_b16 v238, v43 offset:880
	s_and_saveexec_b64 s[6:7], s[42:43]
	s_cbranch_execz .LBB0_894
	v_lshlrev_b32_e32 v128, 2, v118
	v_lshl_add_u64 v[46:47], v[40:41], 0, v[128:129]
	global_store_dwordx4 v[46:47], v[68:71], off offset:32
.LBB0_894:
	s_or_b64 exec, exec, s[6:7]
	v_or_b32_e32 v43, 16, v118
	v_mul_u32_u24_e32 v43, v42, v43
	v_lshlrev_b32_e32 v128, 1, v43
	v_lshl_add_u64 v[46:47], v[44:45], 0, v[128:129]
	v_cvt_pk_bf16_f32 v43, v64, s0
	ds_write_b16 v238, v43 offset:1280
	v_or_b32_e32 v43, 17, v118
	v_mul_u32_u24_e32 v43, v42, v43
	v_lshlrev_b32_e32 v128, 1, v43
	v_lshl_add_u64 v[46:47], v[44:45], 0, v[128:129]
	v_cvt_pk_bf16_f32 v43, v65, s0
	ds_write_b16 v238, v43 offset:1360
	v_or_b32_e32 v43, 18, v118
	v_mul_u32_u24_e32 v43, v42, v43
	v_lshlrev_b32_e32 v128, 1, v43
	v_lshl_add_u64 v[46:47], v[44:45], 0, v[128:129]
	v_cvt_pk_bf16_f32 v43, v66, s0
	ds_write_b16 v238, v43 offset:1440
	v_or_b32_e32 v43, 19, v118
	v_mul_u32_u24_e32 v43, v42, v43
	v_lshlrev_b32_e32 v128, 1, v43
	v_lshl_add_u64 v[46:47], v[44:45], 0, v[128:129]
	v_cvt_pk_bf16_f32 v43, v67, s0
	ds_write_b16 v238, v43 offset:1520
	s_and_saveexec_b64 s[6:7], s[42:43]
	s_cbranch_execz .LBB0_896
	v_lshlrev_b32_e32 v128, 2, v118
	v_lshl_add_u64 v[46:47], v[40:41], 0, v[128:129]
	global_store_dwordx4 v[46:47], v[64:67], off offset:64
.LBB0_896:
	s_or_b64 exec, exec, s[6:7]
	v_or_b32_e32 v43, 24, v118
	v_mul_u32_u24_e32 v43, v42, v43
	v_lshlrev_b32_e32 v128, 1, v43
	v_lshl_add_u64 v[46:47], v[44:45], 0, v[128:129]
	v_cvt_pk_bf16_f32 v43, v56, s0
	ds_write_b16 v238, v43 offset:1920
	v_or_b32_e32 v43, 25, v118
	v_mul_u32_u24_e32 v43, v42, v43
	v_lshlrev_b32_e32 v128, 1, v43
	v_lshl_add_u64 v[46:47], v[44:45], 0, v[128:129]
	v_cvt_pk_bf16_f32 v43, v57, s0
	ds_write_b16 v238, v43 offset:2000
	v_or_b32_e32 v43, 26, v118
	v_mul_u32_u24_e32 v43, v42, v43
	v_lshlrev_b32_e32 v128, 1, v43
	v_lshl_add_u64 v[46:47], v[44:45], 0, v[128:129]
	v_cvt_pk_bf16_f32 v43, v58, s0
	ds_write_b16 v238, v43 offset:2080
	v_or_b32_e32 v43, 27, v118
	v_mul_u32_u24_e32 v43, v42, v43
	v_lshlrev_b32_e32 v128, 1, v43
	v_lshl_add_u64 v[46:47], v[44:45], 0, v[128:129]
	v_cvt_pk_bf16_f32 v43, v59, s0
	ds_write_b16 v238, v43 offset:2160
	s_and_saveexec_b64 s[6:7], s[42:43]
	s_cbranch_execz .LBB0_898
	v_lshlrev_b32_e32 v128, 2, v118
	v_lshl_add_u64 v[46:47], v[40:41], 0, v[128:129]
	global_store_dwordx4 v[46:47], v[56:59], off offset:96
.LBB0_898:
	s_or_b64 exec, exec, s[6:7]
	v_or_b32_e32 v43, 32, v118
	v_mul_u32_u24_e32 v43, v42, v43
	v_lshlrev_b32_e32 v128, 1, v43
	v_lshl_add_u64 v[46:47], v[44:45], 0, v[128:129]
	v_cvt_pk_bf16_f32 v43, v52, s0
	ds_write_b16 v238, v43 offset:2560
	v_or_b32_e32 v43, 33, v118
	v_mul_u32_u24_e32 v43, v42, v43
	v_lshlrev_b32_e32 v128, 1, v43
	v_lshl_add_u64 v[46:47], v[44:45], 0, v[128:129]
	v_cvt_pk_bf16_f32 v43, v53, s0
	ds_write_b16 v238, v43 offset:2640
	v_or_b32_e32 v43, 34, v118
	v_mul_u32_u24_e32 v43, v42, v43
	v_lshlrev_b32_e32 v128, 1, v43
	v_lshl_add_u64 v[46:47], v[44:45], 0, v[128:129]
	v_cvt_pk_bf16_f32 v43, v54, s0
	ds_write_b16 v238, v43 offset:2720
	v_or_b32_e32 v43, 35, v118
	v_mul_u32_u24_e32 v43, v42, v43
	v_lshlrev_b32_e32 v128, 1, v43
	v_lshl_add_u64 v[46:47], v[44:45], 0, v[128:129]
	v_cvt_pk_bf16_f32 v43, v55, s0
	ds_write_b16 v238, v43 offset:2800
	s_and_saveexec_b64 s[6:7], s[42:43]
	s_cbranch_execz .LBB0_900
	v_lshlrev_b32_e32 v128, 2, v118
	v_lshl_add_u64 v[46:47], v[40:41], 0, v[128:129]
	global_store_dwordx4 v[46:47], v[52:55], off offset:128
.LBB0_900:
	s_or_b64 exec, exec, s[6:7]
	v_or_b32_e32 v43, 40, v118
	v_mul_u32_u24_e32 v43, v42, v43
	v_lshlrev_b32_e32 v128, 1, v43
	v_lshl_add_u64 v[46:47], v[44:45], 0, v[128:129]
	v_cvt_pk_bf16_f32 v43, v48, s0
	ds_write_b16 v238, v43 offset:3200
	v_or_b32_e32 v43, 41, v118
	v_mul_u32_u24_e32 v43, v42, v43
	v_lshlrev_b32_e32 v128, 1, v43
	v_lshl_add_u64 v[46:47], v[44:45], 0, v[128:129]
	v_cvt_pk_bf16_f32 v43, v49, s0
	ds_write_b16 v238, v43 offset:3280
	v_or_b32_e32 v43, 42, v118
	v_mul_u32_u24_e32 v43, v42, v43
	v_lshlrev_b32_e32 v128, 1, v43
	v_lshl_add_u64 v[46:47], v[44:45], 0, v[128:129]
	v_cvt_pk_bf16_f32 v43, v50, s0
	ds_write_b16 v238, v43 offset:3360
	v_or_b32_e32 v43, 43, v118
	v_mul_u32_u24_e32 v43, v42, v43
	v_lshlrev_b32_e32 v128, 1, v43
	v_lshl_add_u64 v[46:47], v[44:45], 0, v[128:129]
	v_cvt_pk_bf16_f32 v43, v51, s0
	ds_write_b16 v238, v43 offset:3440
	s_and_saveexec_b64 s[6:7], s[42:43]
	s_cbranch_execz .LBB0_902
	v_lshlrev_b32_e32 v128, 2, v118
	v_lshl_add_u64 v[46:47], v[40:41], 0, v[128:129]
	global_store_dwordx4 v[46:47], v[48:51], off offset:160
.LBB0_902:
	s_or_b64 exec, exec, s[6:7]
	v_or_b32_e32 v43, 48, v118
	v_mul_u32_u24_e32 v43, v42, v43
	v_lshlrev_b32_e32 v128, 1, v43
	v_lshl_add_u64 v[46:47], v[44:45], 0, v[128:129]
	v_cvt_pk_bf16_f32 v43, v36, s0
	ds_write_b16 v238, v43 offset:3840
	v_or_b32_e32 v43, 49, v118
	v_mul_u32_u24_e32 v43, v42, v43
	v_lshlrev_b32_e32 v128, 1, v43
	v_lshl_add_u64 v[46:47], v[44:45], 0, v[128:129]
	v_cvt_pk_bf16_f32 v43, v37, s0
	ds_write_b16 v238, v43 offset:3920
	v_or_b32_e32 v43, 50, v118
	v_mul_u32_u24_e32 v43, v42, v43
	v_lshlrev_b32_e32 v128, 1, v43
	v_lshl_add_u64 v[46:47], v[44:45], 0, v[128:129]
	v_cvt_pk_bf16_f32 v43, v38, s0
	ds_write_b16 v238, v43 offset:4000
	v_or_b32_e32 v43, 51, v118
	v_mul_u32_u24_e32 v43, v42, v43
	v_lshlrev_b32_e32 v128, 1, v43
	v_lshl_add_u64 v[46:47], v[44:45], 0, v[128:129]
	v_cvt_pk_bf16_f32 v43, v39, s0
	ds_write_b16 v238, v43 offset:4080
	s_and_saveexec_b64 s[6:7], s[42:43]
	s_cbranch_execz .LBB0_904
	v_lshlrev_b32_e32 v128, 2, v118
	v_lshl_add_u64 v[46:47], v[40:41], 0, v[128:129]
	global_store_dwordx4 v[46:47], v[36:39], off offset:192
.LBB0_904:
	s_or_b64 exec, exec, s[6:7]
	s_nop 0
	v_or_b32_e32 v36, 56, v118
	v_mul_u32_u24_e32 v36, v42, v36
	v_lshlrev_b32_e32 v128, 1, v36
	v_lshl_add_u64 v[36:37], v[44:45], 0, v[128:129]
	v_cvt_pk_bf16_f32 v38, v32, s0
	ds_write_b16 v238, v38 offset:4480
	v_or_b32_e32 v36, 57, v118
	v_mul_u32_u24_e32 v36, v42, v36
	v_lshlrev_b32_e32 v128, 1, v36
	v_lshl_add_u64 v[36:37], v[44:45], 0, v[128:129]
	v_cvt_pk_bf16_f32 v38, v33, s0
	ds_write_b16 v238, v38 offset:4560
	v_or_b32_e32 v36, 58, v118
	v_mul_u32_u24_e32 v36, v42, v36
	v_lshlrev_b32_e32 v128, 1, v36
	v_lshl_add_u64 v[36:37], v[44:45], 0, v[128:129]
	v_cvt_pk_bf16_f32 v38, v34, s0
	ds_write_b16 v238, v38 offset:4640
	v_or_b32_e32 v36, 59, v118
	v_mul_u32_u24_e32 v36, v42, v36
	v_lshlrev_b32_e32 v128, 1, v36
	v_lshl_add_u64 v[36:37], v[44:45], 0, v[128:129]
	v_cvt_pk_bf16_f32 v38, v35, s0
	ds_write_b16 v238, v38 offset:4720
	s_waitcnt lgkmcnt(0)
	ds_read_b128 v[230:233], v239 offset:0
	ds_read_b128 v[234:237], v239 offset:1280
	ds_read_b128 v[182:185], v239 offset:2560
	ds_read_b128 v[186:189], v239 offset:3840
	s_waitcnt lgkmcnt(3)
	global_store_dwordx4 v[244:245], v[230:233], off
	v_lshl_add_u64 v[244:245], v[244:245], 0, v[246:247]
	s_waitcnt lgkmcnt(2)
	global_store_dwordx4 v[244:245], v[234:237], off
	v_lshl_add_u64 v[244:245], v[244:245], 0, v[246:247]
	s_waitcnt lgkmcnt(1)
	global_store_dwordx4 v[244:245], v[182:185], off
	v_lshl_add_u64 v[244:245], v[244:245], 0, v[246:247]
	s_waitcnt lgkmcnt(0)
	global_store_dwordx4 v[244:245], v[186:189], off
	s_and_saveexec_b64 s[6:7], s[42:43]
	s_cbranch_execz .LBB0_906
	v_lshlrev_b32_e32 v128, 2, v118
	v_lshl_add_u64 v[36:37], v[40:41], 0, v[128:129]
	global_store_dwordx4 v[36:37], v[32:35], off offset:224

.LBB0_930:
	s_or_b64 exec, exec, s[2:3]
	v_add_u32_e32 v49, 0xfffff040, v116
	v_xor_b32_e32 v33, s27, v49
	s_movk_i32 s2, 0x400
	v_cmp_gt_u32_e64 s[42:43], s2, v33
	s_and_b64 s[2:3], s[14:15], s[42:43]
	v_cndmask_b32_e64 v33, 0, 1, s[2:3]
	s_movk_i32 s2, 0xfc0
	v_cmp_gt_i32_e64 s[42:43], s2, v116
	v_add_u32_e32 v48, 64, v116
	v_subrev_u32_e32 v32, s26, v48
	v_cndmask_b32_e64 v33, v33, v121, s[42:43]
	v_and_b32_e32 v33, 1, v33
	v_cmp_eq_u32_e64 s[44:45], 1, v33
	v_lshl_add_u32 v32, v32, 2, v167
	s_movk_i32 s2, 0xfbf
	v_cndmask_b32_e64 v33, v171, 0, s[44:45]
	v_add_u32_e32 v55, v120, v33
	ds_read_b32 v54, v32
	ds_read_b128 v[32:35], v55
	ds_read_b128 v[36:39], v55 offset:32
	ds_read_b128 v[50:53], v55 offset:64
	v_cmp_lt_i32_e64 s[44:45], s2, v116
	s_waitcnt lgkmcnt(2)
	v_pk_fma_f32 v[44:45], v[0:1], v[54:55], v[32:33] op_sel_hi:[1,0,1]
	v_pk_fma_f32 v[46:47], v[2:3], v[54:55], v[34:35] op_sel_hi:[1,0,1]
	s_waitcnt lgkmcnt(1)
	v_pk_fma_f32 v[40:41], v[4:5], v[54:55], v[36:37] op_sel_hi:[1,0,1]
	ds_read_b128 v[0:3], v55 offset:96
	v_pk_fma_f32 v[42:43], v[6:7], v[54:55], v[38:39] op_sel_hi:[1,0,1]
	ds_read_b128 v[4:7], v55 offset:128
	s_waitcnt lgkmcnt(2)
	v_pk_fma_f32 v[36:37], v[8:9], v[54:55], v[50:51] op_sel_hi:[1,0,1]
	v_pk_fma_f32 v[38:39], v[10:11], v[54:55], v[52:53] op_sel_hi:[1,0,1]
	s_waitcnt lgkmcnt(1)
	v_pk_fma_f32 v[32:33], v[12:13], v[54:55], v[0:1] op_sel_hi:[1,0,1]
	v_pk_fma_f32 v[34:35], v[14:15], v[54:55], v[2:3] op_sel_hi:[1,0,1]
	ds_read_b128 v[0:3], v55 offset:160
	s_waitcnt lgkmcnt(1)
	v_pk_fma_f32 v[12:13], v[16:17], v[54:55], v[4:5] op_sel_hi:[1,0,1]
	ds_read_b128 v[50:53], v55 offset:192
	v_pk_fma_f32 v[14:15], v[18:19], v[54:55], v[6:7] op_sel_hi:[1,0,1]
	ds_read_b128 v[16:19], v55 offset:224
	s_waitcnt lgkmcnt(2)
	v_pk_fma_f32 v[8:9], v[20:21], v[54:55], v[0:1] op_sel_hi:[1,0,1]
	v_pk_fma_f32 v[10:11], v[22:23], v[54:55], v[2:3] op_sel_hi:[1,0,1]
	s_waitcnt lgkmcnt(1)
	v_pk_fma_f32 v[4:5], v[24:25], v[54:55], v[50:51] op_sel_hi:[1,0,1]
	v_pk_fma_f32 v[6:7], v[26:27], v[54:55], v[52:53] op_sel_hi:[1,0,1]
	s_waitcnt lgkmcnt(0)
	v_pk_fma_f32 v[0:1], v[28:29], v[54:55], v[16:17] op_sel_hi:[1,0,1]
	v_pk_fma_f32 v[2:3], v[30:31], v[54:55], v[18:19] op_sel_hi:[1,0,1]
	s_and_saveexec_b64 s[2:3], s[40:41]
	s_xor_b64 s[2:3], exec, s[2:3]
	s_cbranch_execz .LBB0_976
	s_and_saveexec_b64 s[4:5], s[0:1]
	s_xor_b64 s[0:1], exec, s[4:5]
	s_cbranch_execz .LBB0_955
	v_mov_b64_e32 v[16:17], 0
	s_and_saveexec_b64 s[4:5], s[42:43]
	v_lshrrev_b32_e32 v16, 7, v48
	v_and_b32_e32 v16, 0xfffffe, v16
	v_add_u32_e32 v16, s48, v16
	s_mov_b32 s6, 0x6050400
	v_perm_b32 v16, v16, v48, s6
	v_ashrrev_i32_e32 v17, 31, v16
	v_lshlrev_b64 v[16:17], 11, v[16:17]
	v_lshl_add_u64 v[16:17], s[62:63], 0, v[16:17]
	v_lshl_add_u64 v[16:17], v[110:111], 2, v[16:17]
	s_or_b64 exec, exec, s[4:5]
	s_and_saveexec_b64 s[4:5], s[44:45]
	s_xor_b64 s[4:5], exec, s[4:5]
	v_lshrrev_b32_e32 v18, 7, v49
	v_and_b32_e32 v24, 0x1fffff8, v18
	s_or_saveexec_b64 s[4:5], s[4:5]
	v_mov_b64_e32 v[18:19], 0x400
	v_mov_b32_e32 v19, 0x3ff
	v_mov_b64_e32 v[20:21], 0xdf94000
	v_mov_b64_e32 v[22:23], 17
	s_xor_b64 exec, exec, s[4:5]
	v_ashrrev_i32_e32 v18, 5, v48
	v_and_b32_e32 v24, -8, v18
	v_mov_b64_e32 v[18:19], 0x100
	v_mov_b32_e32 v19, 0xff
	v_mov_b64_e32 v[20:21], 0xdb94000
	v_mov_b64_e32 v[22:23], 15
	s_or_b64 exec, exec, s[4:5]
	v_add_u32_e32 v24, v24, v119
	v_ashrrev_i32_e32 v25, 31, v24
	v_lshl_add_u64 v[20:21], s[50:51], 0, v[20:21]
	v_lshlrev_b64 v[22:23], v22, v[24:25]
	v_and_b32_e32 v19, v19, v48
	v_lshl_add_u64 v[20:21], v[20:21], 0, v[22:23]
	v_lshlrev_b32_e32 v128, 1, v19
	v_mul_u32_u24_e32 v19, v18, v118
	v_lshl_add_u64 v[20:21], v[20:21], 0, v[128:129]
	v_lshlrev_b32_e32 v128, 1, v19
	v_lshl_add_u64 v[22:23], v[20:21], 0, v[128:129]
	v_cvt_pk_bf16_f32 v19, v44, s0
	v_and_b32_e32 v240, 31, v155
	v_lshrrev_b32_e32 v239, 6, v155
	v_mul_u32_u24_e32 v239, 0x1400, v239
	v_bfe_u32 v246, v155, 5, 1
	v_mul_u32_u24_e32 v246, 0x140, v246
	v_lshl_add_u32 v238, v240, 1, v239
	v_add_u32_e32 v238, v238, v246
	v_bfe_u32 v246, v155, 2, 4
	v_mul_u32_u24_e32 v247, 0x50, v246
	v_add_u32_e32 v239, v239, v247
	v_mul_u32_u24_e32 v246, v18, v246
	v_and_b32_e32 v247, 3, v155
	v_lshl_add_u32 v239, v247, 4, v239
	v_lshlrev_b32_e32 v247, 4, v247
	v_lshl_add_u32 v246, v246, 1, v247
	v_lshlrev_b32_e32 v240, 1, v240
	v_sub_u32_e32 v246, v246, v240
	v_ashrrev_i32_e32 v247, 31, v246
	v_lshl_add_u64 v[244:245], v[20:21], 0, v[246:247]
	v_lshlrev_b32_e32 v246, 5, v18
	v_mov_b32_e32 v247, 0
	ds_write_b16 v238, v19
	v_or_b32_e32 v19, 1, v118
	v_mul_u32_u24_e32 v19, v18, v19
	v_lshlrev_b32_e32 v128, 1, v19
	v_lshl_add_u64 v[22:23], v[20:21], 0, v[128:129]
	v_cvt_pk_bf16_f32 v19, v45, s0
	ds_write_b16 v238, v19 offset:80
	v_or_b32_e32 v19, 2, v118
	v_mul_u32_u24_e32 v19, v18, v19
	v_lshlrev_b32_e32 v128, 1, v19
	v_lshl_add_u64 v[22:23], v[20:21], 0, v[128:129]
	v_cvt_pk_bf16_f32 v19, v46, s0
	ds_write_b16 v238, v19 offset:160
	v_or_b32_e32 v19, 3, v118
	v_mul_u32_u24_e32 v19, v18, v19
	v_lshlrev_b32_e32 v128, 1, v19
	v_lshl_add_u64 v[22:23], v[20:21], 0, v[128:129]
	v_cvt_pk_bf16_f32 v19, v47, s0
	ds_write_b16 v238, v19 offset:240
	s_and_saveexec_b64 s[4:5], s[42:43]
	s_cbranch_execz .LBB0_940
	v_lshlrev_b32_e32 v128, 2, v118
	v_lshl_add_u64 v[22:23], v[16:17], 0, v[128:129]
	global_store_dwordx4 v[22:23], v[44:47], off
.LBB0_940:
	s_or_b64 exec, exec, s[4:5]
	v_or_b32_e32 v19, 8, v118
	v_mul_u32_u24_e32 v19, v18, v19
	v_lshlrev_b32_e32 v128, 1, v19
	v_lshl_add_u64 v[22:23], v[20:21], 0, v[128:129]
	v_cvt_pk_bf16_f32 v19, v40, s0
	ds_write_b16 v238, v19 offset:640
	v_or_b32_e32 v19, 9, v118
	v_mul_u32_u24_e32 v19, v18, v19
	v_lshlrev_b32_e32 v128, 1, v19
	v_lshl_add_u64 v[22:23], v[20:21], 0, v[128:129]
	v_cvt_pk_bf16_f32 v19, v41, s0
	ds_write_b16 v238, v19 offset:720
	v_or_b32_e32 v19, 10, v118
	v_mul_u32_u24_e32 v19, v18, v19
	v_lshlrev_b32_e32 v128, 1, v19
	v_lshl_add_u64 v[22:23], v[20:21], 0, v[128:129]
	v_cvt_pk_bf16_f32 v19, v42, s0
	ds_write_b16 v238, v19 offset:800
	v_or_b32_e32 v19, 11, v118
	v_mul_u32_u24_e32 v19, v18, v19
	v_lshlrev_b32_e32 v128, 1, v19
	v_lshl_add_u64 v[22:23], v[20:21], 0, v[128:129]
	v_cvt_pk_bf16_f32 v19, v43, s0
	ds_write_b16 v238, v19 offset:880
	s_and_saveexec_b64 s[4:5], s[42:43]
	s_cbranch_execz .LBB0_942
	v_lshlrev_b32_e32 v128, 2, v118
	v_lshl_add_u64 v[22:23], v[16:17], 0, v[128:129]
	global_store_dwordx4 v[22:23], v[40:43], off offset:32
.LBB0_942:
	s_or_b64 exec, exec, s[4:5]
	v_or_b32_e32 v19, 16, v118
	v_mul_u32_u24_e32 v19, v18, v19
	v_lshlrev_b32_e32 v128, 1, v19
	v_lshl_add_u64 v[22:23], v[20:21], 0, v[128:129]
	v_cvt_pk_bf16_f32 v19, v36, s0
	ds_write_b16 v238, v19 offset:1280
	v_or_b32_e32 v19, 17, v118
	v_mul_u32_u24_e32 v19, v18, v19
	v_lshlrev_b32_e32 v128, 1, v19
	v_lshl_add_u64 v[22:23], v[20:21], 0, v[128:129]
	v_cvt_pk_bf16_f32 v19, v37, s0
	ds_write_b16 v238, v19 offset:1360
	v_or_b32_e32 v19, 18, v118
	v_mul_u32_u24_e32 v19, v18, v19
	v_lshlrev_b32_e32 v128, 1, v19
	v_lshl_add_u64 v[22:23], v[20:21], 0, v[128:129]
	v_cvt_pk_bf16_f32 v19, v38, s0
	ds_write_b16 v238, v19 offset:1440
	v_or_b32_e32 v19, 19, v118
	v_mul_u32_u24_e32 v19, v18, v19
	v_lshlrev_b32_e32 v128, 1, v19
	v_lshl_add_u64 v[22:23], v[20:21], 0, v[128:129]
	v_cvt_pk_bf16_f32 v19, v39, s0
	ds_write_b16 v238, v19 offset:1520
	s_and_saveexec_b64 s[4:5], s[42:43]
	s_cbranch_execz .LBB0_944
	v_lshlrev_b32_e32 v128, 2, v118
	v_lshl_add_u64 v[22:23], v[16:17], 0, v[128:129]
	global_store_dwordx4 v[22:23], v[36:39], off offset:64
.LBB0_944:
	s_or_b64 exec, exec, s[4:5]
	v_or_b32_e32 v19, 24, v118
	v_mul_u32_u24_e32 v19, v18, v19
	v_lshlrev_b32_e32 v128, 1, v19
	v_lshl_add_u64 v[22:23], v[20:21], 0, v[128:129]
	v_cvt_pk_bf16_f32 v19, v32, s0
	ds_write_b16 v238, v19 offset:1920
	v_or_b32_e32 v19, 25, v118
	v_mul_u32_u24_e32 v19, v18, v19
	v_lshlrev_b32_e32 v128, 1, v19
	v_lshl_add_u64 v[22:23], v[20:21], 0, v[128:129]
	v_cvt_pk_bf16_f32 v19, v33, s0
	ds_write_b16 v238, v19 offset:2000
	v_or_b32_e32 v19, 26, v118
	v_mul_u32_u24_e32 v19, v18, v19
	v_lshlrev_b32_e32 v128, 1, v19
	v_lshl_add_u64 v[22:23], v[20:21], 0, v[128:129]
	v_cvt_pk_bf16_f32 v19, v34, s0
	ds_write_b16 v238, v19 offset:2080
	v_or_b32_e32 v19, 27, v118
	v_mul_u32_u24_e32 v19, v18, v19
	v_lshlrev_b32_e32 v128, 1, v19
	v_lshl_add_u64 v[22:23], v[20:21], 0, v[128:129]
	v_cvt_pk_bf16_f32 v19, v35, s0
	ds_write_b16 v238, v19 offset:2160
	s_and_saveexec_b64 s[4:5], s[42:43]
	s_cbranch_execz .LBB0_946
	v_lshlrev_b32_e32 v128, 2, v118
	v_lshl_add_u64 v[22:23], v[16:17], 0, v[128:129]
	global_store_dwordx4 v[22:23], v[32:35], off offset:96
.LBB0_946:
	s_or_b64 exec, exec, s[4:5]
	v_or_b32_e32 v19, 32, v118
	v_mul_u32_u24_e32 v19, v18, v19
	v_lshlrev_b32_e32 v128, 1, v19
	v_lshl_add_u64 v[22:23], v[20:21], 0, v[128:129]
	v_cvt_pk_bf16_f32 v19, v12, s0
	ds_write_b16 v238, v19 offset:2560
	v_or_b32_e32 v19, 33, v118
	v_mul_u32_u24_e32 v19, v18, v19
	v_lshlrev_b32_e32 v128, 1, v19
	v_lshl_add_u64 v[22:23], v[20:21], 0, v[128:129]
	v_cvt_pk_bf16_f32 v19, v13, s0
	ds_write_b16 v238, v19 offset:2640
	v_or_b32_e32 v19, 34, v118
	v_mul_u32_u24_e32 v19, v18, v19
	v_lshlrev_b32_e32 v128, 1, v19
	v_lshl_add_u64 v[22:23], v[20:21], 0, v[128:129]
	v_cvt_pk_bf16_f32 v19, v14, s0
	ds_write_b16 v238, v19 offset:2720
	v_or_b32_e32 v19, 35, v118
	v_mul_u32_u24_e32 v19, v18, v19
	v_lshlrev_b32_e32 v128, 1, v19
	v_lshl_add_u64 v[22:23], v[20:21], 0, v[128:129]
	v_cvt_pk_bf16_f32 v19, v15, s0
	ds_write_b16 v238, v19 offset:2800
	s_and_saveexec_b64 s[4:5], s[42:43]
	s_cbranch_execz .LBB0_948
	v_lshlrev_b32_e32 v128, 2, v118
	v_lshl_add_u64 v[22:23], v[16:17], 0, v[128:129]
	global_store_dwordx4 v[22:23], v[12:15], off offset:128
.LBB0_948:
	s_or_b64 exec, exec, s[4:5]
	s_nop 0
	v_or_b32_e32 v12, 40, v118
	v_mul_u32_u24_e32 v12, v18, v12
	v_lshlrev_b32_e32 v128, 1, v12
	v_lshl_add_u64 v[12:13], v[20:21], 0, v[128:129]
	v_cvt_pk_bf16_f32 v14, v8, s0
	ds_write_b16 v238, v14 offset:3200
	v_or_b32_e32 v12, 41, v118
	v_mul_u32_u24_e32 v12, v18, v12
	v_lshlrev_b32_e32 v128, 1, v12
	v_lshl_add_u64 v[12:13], v[20:21], 0, v[128:129]
	v_cvt_pk_bf16_f32 v14, v9, s0
	ds_write_b16 v238, v14 offset:3280
	v_or_b32_e32 v12, 42, v118
	v_mul_u32_u24_e32 v12, v18, v12
	v_lshlrev_b32_e32 v128, 1, v12
	v_lshl_add_u64 v[12:13], v[20:21], 0, v[128:129]
	v_cvt_pk_bf16_f32 v14, v10, s0
	ds_write_b16 v238, v14 offset:3360
	v_or_b32_e32 v12, 43, v118
	v_mul_u32_u24_e32 v12, v18, v12
	v_lshlrev_b32_e32 v128, 1, v12
	v_lshl_add_u64 v[12:13], v[20:21], 0, v[128:129]
	v_cvt_pk_bf16_f32 v14, v11, s0
	ds_write_b16 v238, v14 offset:3440
	s_and_saveexec_b64 s[4:5], s[42:43]
	s_cbranch_execz .LBB0_950
	v_lshlrev_b32_e32 v128, 2, v118
	v_lshl_add_u64 v[12:13], v[16:17], 0, v[128:129]
	global_store_dwordx4 v[12:13], v[8:11], off offset:160
.LBB0_950:
	s_or_b64 exec, exec, s[4:5]
	s_nop 0
	v_or_b32_e32 v8, 48, v118
	v_mul_u32_u24_e32 v8, v18, v8
	v_lshlrev_b32_e32 v128, 1, v8
	v_lshl_add_u64 v[8:9], v[20:21], 0, v[128:129]
	v_cvt_pk_bf16_f32 v10, v4, s0
	ds_write_b16 v238, v10 offset:3840
	v_or_b32_e32 v8, 49, v118
	v_mul_u32_u24_e32 v8, v18, v8
	v_lshlrev_b32_e32 v128, 1, v8
	v_lshl_add_u64 v[8:9], v[20:21], 0, v[128:129]
	v_cvt_pk_bf16_f32 v10, v5, s0
	ds_write_b16 v238, v10 offset:3920
	v_or_b32_e32 v8, 50, v118
	v_mul_u32_u24_e32 v8, v18, v8
	v_lshlrev_b32_e32 v128, 1, v8
	v_lshl_add_u64 v[8:9], v[20:21], 0, v[128:129]
	v_cvt_pk_bf16_f32 v10, v6, s0
	ds_write_b16 v238, v10 offset:4000
	v_or_b32_e32 v8, 51, v118
	v_mul_u32_u24_e32 v8, v18, v8
	v_lshlrev_b32_e32 v128, 1, v8
	v_lshl_add_u64 v[8:9], v[20:21], 0, v[128:129]
	v_cvt_pk_bf16_f32 v10, v7, s0
	ds_write_b16 v238, v10 offset:4080
	s_and_saveexec_b64 s[4:5], s[42:43]
	s_cbranch_execz .LBB0_952
	v_lshlrev_b32_e32 v128, 2, v118
	v_lshl_add_u64 v[8:9], v[16:17], 0, v[128:129]
	global_store_dwordx4 v[8:9], v[4:7], off offset:192
.LBB0_952:
	s_or_b64 exec, exec, s[4:5]
	s_nop 0
	v_or_b32_e32 v4, 56, v118
	v_mul_u32_u24_e32 v4, v18, v4
	v_lshlrev_b32_e32 v128, 1, v4
	v_lshl_add_u64 v[4:5], v[20:21], 0, v[128:129]
	v_cvt_pk_bf16_f32 v6, v0, s0
	ds_write_b16 v238, v6 offset:4480
	v_or_b32_e32 v4, 57, v118
	v_mul_u32_u24_e32 v4, v18, v4
	v_lshlrev_b32_e32 v128, 1, v4
	v_lshl_add_u64 v[4:5], v[20:21], 0, v[128:129]
	v_cvt_pk_bf16_f32 v6, v1, s0
	ds_write_b16 v238, v6 offset:4560
	v_or_b32_e32 v4, 58, v118
	v_mul_u32_u24_e32 v4, v18, v4
	v_lshlrev_b32_e32 v128, 1, v4
	v_lshl_add_u64 v[4:5], v[20:21], 0, v[128:129]
	v_cvt_pk_bf16_f32 v6, v2, s0
	ds_write_b16 v238, v6 offset:4640
	v_or_b32_e32 v4, 59, v118
	v_mul_u32_u24_e32 v4, v18, v4
	v_lshlrev_b32_e32 v128, 1, v4
	v_lshl_add_u64 v[4:5], v[20:21], 0, v[128:129]
	v_cvt_pk_bf16_f32 v6, v3, s0
	ds_write_b16 v238, v6 offset:4720
	s_waitcnt lgkmcnt(0)
	ds_read_b128 v[230:233], v239 offset:0
	ds_read_b128 v[234:237], v239 offset:1280
	ds_read_b128 v[182:185], v239 offset:2560
	ds_read_b128 v[186:189], v239 offset:3840
	s_waitcnt lgkmcnt(3)
	global_store_dwordx4 v[244:245], v[230:233], off
	v_lshl_add_u64 v[244:245], v[244:245], 0, v[246:247]
	s_waitcnt lgkmcnt(2)
	global_store_dwordx4 v[244:245], v[234:237], off
	v_lshl_add_u64 v[244:245], v[244:245], 0, v[246:247]
	s_waitcnt lgkmcnt(1)
	global_store_dwordx4 v[244:245], v[182:185], off
	v_lshl_add_u64 v[244:245], v[244:245], 0, v[246:247]
	s_waitcnt lgkmcnt(0)
	global_store_dwordx4 v[244:245], v[186:189], off
	s_and_saveexec_b64 s[4:5], s[42:43]
	s_cbranch_execz .LBB0_954
	v_lshlrev_b32_e32 v128, 2, v118
	v_lshl_add_u64 v[4:5], v[16:17], 0, v[128:129]
	global_store_dwordx4 v[4:5], v[0:3], off offset:224
